# speedup vs baseline: 1.0137x; 1.0137x over previous
; __device__ __forceinline__ int tid_opaque() { int t = threadIdx.x; asm volatile("" : "+v"(t)); return t; }
; template <int K, bool SRC_F32>
; __device__ __forceinline__ void ctx_small_gemm(const bf16* __restrict__ WT, const bf16* __restrict__ act, const float* __restrict__ gate4,
;                                                const float* __restrict__ srcf, bf16* __restrict__ xbc) {
;   const int tid = tid_opaque(), wid = tid >> 6, lane = tid & 63, r32 = lane & 31, hi = lane >> 5;
;   const int kh = wid >> 2, ob = wid & 3, tb = ob >> 1, fb = ob & 1;
;   float* red = (float*)shm_raw;
;   for (int it = blockIdx.x; it < 256; it += gridDim.x) {
;     const int tok0 = (it >> 4) * 64 + tb * 32, f0 = (it & 15) * 64 + fb * 32;
;     const bf16* ap = act + (size_t)(tok0 + r32) * K + kh * (K / 2) + hi * 8;
;     const bf16* bp = WT + (size_t)(f0 + r32) * K + kh * (K / 2) + hi * 8;
.LBB0_996:
	s_cmpk_lt_i32 s71, 0x100
	v_mov_b32_e32 v0, v192
	s_cselect_b64 s[0:1], -1, 0
	s_cmpk_gt_i32 s71, 0xff
	s_movk_i32 s2, 0x100
	s_cbranch_scc1 .LBB0_1005
	v_and_b32_e32 v1, 63, v0
	v_lshl_add_u32 v5, v1, 2, 0
	v_ashrrev_i32_e32 v1, 8, v0
	v_lshrrev_b32_e32 v2, 2, v0
	v_and_b32_e32 v26, 32, v2
	v_lshlrev_b32_e32 v2, 9, v1
	s_waitcnt lgkmcnt(0)
	s_add_u32 s10, s8, 0x305a000
	s_load_dwordx2 s[12:13], s[4:5], 0x10
	v_and_b32_e32 v4, 31, v0
	v_bfe_u32 v6, v0, 5, 1
	v_lshrrev_b32_e32 v7, 1, v0
	v_ashrrev_i32_e32 v3, 31, v2
	v_cmp_gt_u32_e64 s[4:5], s2, v0
	v_lshlrev_b32_e32 v0, 6, v0
	s_addc_u32 s11, s9, 0
	v_cmp_eq_u32_e32 vcc, 1, v1
	v_and_b32_e32 v8, 0xfffff000, v0
	v_and_b32_e32 v9, 0x3000, v0
	v_lshlrev_b64 v[0:1], 1, v[2:3]
	s_add_u32 s14, s8, 0xb300100
	v_lshl_or_b32 v0, v6, 4, v0
	s_addc_u32 s15, s9, 0
	v_lshl_add_u64 v[0:1], s[8:9], 0, v[0:1]
	v_lshrrev_b32_e32 v140, 4, v192
	v_xor_b32_e32 v141, v140, v192
	v_and_b32_e32 v141, 15, v141
	v_lshlrev_b32_e32 v141, 4, v141
	v_mov_b32_e32 v162, 0x800
	v_mad_u32_u24 v140, v140, v162, v141
	v_mov_b32_e32 v141, 0
	v_lshl_add_u64 v[142:143], s[8:9], 0, v[140:141]
	v_lshl_add_u64 v[144:145], s[8:9], 0, v[140:141]
	v_mov_b32_e32 v162, 0x7100100
	v_mov_b32_e32 v163, 0
	v_lshl_add_u64 v[142:143], v[142:143], 0, v[162:163]
	v_mov_b32_e32 v162, 0xb00000
	v_lshl_add_u64 v[144:145], v[144:145], 0, v[162:163]
	v_and_b32_e32 v162, 31, v192
	v_bfe_u32 v163, v192, 5, 1
	v_lshrrev_b32_e32 v164, 8, v192
	v_bfe_u32 v165, v192, 7, 1
	v_bfe_u32 v166, v192, 6, 1
	v_and_b32_e32 v167, 15, v162
	v_lshlrev_b32_e32 v167, 4, v167
	v_lshlrev_b32_e32 v168, 7, v164
	v_lshl_or_b32 v168, v163, 4, v168
	v_xor_b32_e32 v167, v167, v168
	v_lshl_or_b32 v169, v165, 5, v162
	v_lshl_or_b32 v154, v169, 8, v167
	v_lshl_or_b32 v169, v166, 5, v162
	v_lshl_or_b32 v158, v169, 8, v167
	v_add_u32_e32 v158, 0x4000, v158
	v_xor_b32_e32 v155, 32, v154
	v_xor_b32_e32 v159, 32, v158
	v_xor_b32_e32 v156, 64, v154
	v_xor_b32_e32 v160, 64, v158
	v_xor_b32_e32 v157, 96, v154
	v_xor_b32_e32 v161, 96, v158
	v_add_u32_e32 v170, 0x10000, v154
	v_add_u32_e32 v171, 0x10000, v155
	v_add_u32_e32 v172, 0x10000, v156
	v_add_u32_e32 v173, 0x10000, v157
	v_add_u32_e32 v174, 0x10000, v158
	v_add_u32_e32 v175, 0x10000, v159
	v_add_u32_e32 v176, 0x10000, v160
	v_add_u32_e32 v177, 0x10000, v161
	s_mov_b64 s[2:3], 0x7100180
	s_mov_b64 s[8:9], 0xb00080
	v_lshlrev_b32_e32 v27, 2, v6
	v_and_or_b32 v28, v7, 32, v4
	v_lshl_add_u64 v[16:17], v[0:1], 0, s[2:3]
	v_or_b32_e32 v29, v26, v4
	s_lshl_b32 s2, s71, 2
	s_lshl_b32 s3, s74, 2
	v_lshl_add_u64 v[18:19], v[0:1], 0, s[8:9]
	s_lshl_b32 s18, s71, 6
	s_lshl_b32 s19, s74, 6
	v_mov_b32_e32 v21, 0
	s_mov_b64 s[8:9], 0x100
	v_add_u32_e32 v30, v5, v9
	v_add_u32_e32 v31, v5, v8
	s_mov_b32 s20, s71
	s_branch .LBB0_999

; template <int K, bool SRC_F32>
; __device__ __forceinline__ void ctx_small_gemm(const bf16* __restrict__ WT, const bf16* __restrict__ act, const float* __restrict__ gate4,
;                                                const float* __restrict__ srcf, bf16* __restrict__ xbc) {
;     ...
;     const int tok0 = (it >> 4) * 64 + tb * 32, f0 = (it & 15) * 64 + fb * 32;
;     const bf16* ap = act + (size_t)(tok0 + r32) * K + kh * (K / 2) + hi * 8;
;     const bf16* bp = WT + (size_t)(f0 + r32) * K + kh * (K / 2) + hi * 8;
;     f32x16 acc = {};
; #pragma unroll 8
;     for (int k = 0; k < K / 2; k += 16) {
;       bf16x8 a = *reinterpret_cast<const bf16x8*>(ap + k), b = *reinterpret_cast<const bf16x8*>(bp + k);
;       acc = __builtin_amdgcn_mfma_f32_32x32x16_bf16(a, b, acc, 0, 0, 0);
;     }
.LBB0_1000:
	s_and_b32 s16, s2, 0xffffffc0
	s_mul_i32 s16, s16, 0x800
	s_mov_b32 s17, 0
	v_lshl_add_u64 v[146:147], v[142:143], 0, s[16:17]
	s_lshl_b32 s16, s20, 6
	s_and_b32 s16, s16, 0x3c0
	s_mul_i32 s16, s16, 0x800
	v_lshl_add_u64 v[150:151], v[144:145], 0, s[16:17]
	s_mov_b32 s16, 0x10000
	v_lshl_add_u64 v[148:149], v[146:147], 0, s[16:17]
	v_lshl_add_u64 v[152:153], v[150:151], 0, s[16:17]
	v_lshrrev_b32_e32 v162, 6, v192
	v_lshlrev_b32_e32 v162, 10, v162
	s_nop 0
	v_readfirstlane_b32 s21, v162
	s_nop 3
	s_add_u32 m0, s21, 0x4000
	s_nop 0
	global_load_lds_dwordx4 v[146:147], off
	s_add_u32 m0, s21, 0x6000
	s_nop 0
	global_load_lds_dwordx4 v[148:149], off
	s_add_u32 m0, s21, 0x8000
	s_nop 0
	global_load_lds_dwordx4 v[150:151], off
	s_add_u32 m0, s21, 0xa000
	s_nop 0
	global_load_lds_dwordx4 v[152:153], off
	v_lshl_add_u64 v[146:147], v[146:147], 0, s[8:9]
	v_lshl_add_u64 v[148:149], v[148:149], 0, s[8:9]
	v_lshl_add_u64 v[150:151], v[150:151], 0, s[8:9]
	v_lshl_add_u64 v[152:153], v[152:153], 0, s[8:9]
	s_add_u32 m0, s21, 0xc000
	s_nop 0
	global_load_lds_dwordx4 v[146:147], off
	s_add_u32 m0, s21, 0xe000
	s_nop 0
	global_load_lds_dwordx4 v[148:149], off
	s_add_u32 m0, s21, 0x10000
	s_nop 0
	global_load_lds_dwordx4 v[150:151], off
	s_add_u32 m0, s21, 0x12000
	s_nop 0
	global_load_lds_dwordx4 v[152:153], off
	v_lshl_add_u64 v[146:147], v[146:147], 0, s[8:9]
	v_lshl_add_u64 v[148:149], v[148:149], 0, s[8:9]
	v_lshl_add_u64 v[150:151], v[150:151], 0, s[8:9]
	v_lshl_add_u64 v[152:153], v[152:153], 0, s[8:9]
	s_waitcnt vmcnt(4)
	s_barrier
	s_add_u32 m0, s21, 0x14000
	s_nop 0
	global_load_lds_dwordx4 v[146:147], off
	s_add_u32 m0, s21, 0x16000
	s_nop 0
	global_load_lds_dwordx4 v[148:149], off
	s_add_u32 m0, s21, 0x18000
	s_nop 0
	global_load_lds_dwordx4 v[150:151], off
	s_add_u32 m0, s21, 0x1a000
	s_nop 0
	global_load_lds_dwordx4 v[152:153], off
	v_lshl_add_u64 v[146:147], v[146:147], 0, s[8:9]
	v_lshl_add_u64 v[148:149], v[148:149], 0, s[8:9]
	v_lshl_add_u64 v[150:151], v[150:151], 0, s[8:9]
	v_lshl_add_u64 v[152:153], v[152:153], 0, s[8:9]
	ds_read_b128 v[32:35], v154 offset:16384
	ds_read_b128 v[36:39], v158 offset:16384
	ds_read_b128 v[40:43], v155 offset:16384
	ds_read_b128 v[44:47], v159 offset:16384
	ds_read_b128 v[48:51], v156 offset:16384
	ds_read_b128 v[52:55], v160 offset:16384
	ds_read_b128 v[56:59], v157 offset:16384
	ds_read_b128 v[60:63], v161 offset:16384
	s_waitcnt lgkmcnt(6)
	v_mfma_f32_32x32x16_bf16 v[0:15], v[32:35], v[36:39], v[0:15]
	s_waitcnt lgkmcnt(4)
	v_mfma_f32_32x32x16_bf16 v[0:15], v[40:43], v[44:47], v[0:15]
	s_waitcnt lgkmcnt(2)
	v_mfma_f32_32x32x16_bf16 v[0:15], v[48:51], v[52:55], v[0:15]
	s_waitcnt lgkmcnt(0)
	v_mfma_f32_32x32x16_bf16 v[0:15], v[56:59], v[60:63], v[0:15]
	s_waitcnt vmcnt(4)
	s_barrier
	s_add_u32 m0, s21, 0x4000
	s_nop 0
	global_load_lds_dwordx4 v[146:147], off
	s_add_u32 m0, s21, 0x6000
	s_nop 0
	global_load_lds_dwordx4 v[148:149], off
	s_add_u32 m0, s21, 0x8000
	s_nop 0
	global_load_lds_dwordx4 v[150:151], off
	s_add_u32 m0, s21, 0xa000
	s_nop 0
	global_load_lds_dwordx4 v[152:153], off
	v_lshl_add_u64 v[146:147], v[146:147], 0, s[8:9]
	v_lshl_add_u64 v[148:149], v[148:149], 0, s[8:9]
	v_lshl_add_u64 v[150:151], v[150:151], 0, s[8:9]
	v_lshl_add_u64 v[152:153], v[152:153], 0, s[8:9]
	ds_read_b128 v[32:35], v154 offset:49152
	ds_read_b128 v[36:39], v158 offset:49152
	ds_read_b128 v[40:43], v155 offset:49152
	ds_read_b128 v[44:47], v159 offset:49152
	ds_read_b128 v[48:51], v156 offset:49152
	ds_read_b128 v[52:55], v160 offset:49152
	ds_read_b128 v[56:59], v157 offset:49152
	ds_read_b128 v[60:63], v161 offset:49152
	s_waitcnt lgkmcnt(6)
	v_mfma_f32_32x32x16_bf16 v[0:15], v[32:35], v[36:39], v[0:15]
	s_waitcnt lgkmcnt(4)
	v_mfma_f32_32x32x16_bf16 v[0:15], v[40:43], v[44:47], v[0:15]
	s_waitcnt lgkmcnt(2)
	v_mfma_f32_32x32x16_bf16 v[0:15], v[48:51], v[52:55], v[0:15]
	s_waitcnt lgkmcnt(0)
	v_mfma_f32_32x32x16_bf16 v[0:15], v[56:59], v[60:63], v[0:15]
	s_waitcnt vmcnt(4)
	s_barrier
	s_add_u32 m0, s21, 0xc000
	s_nop 0
	global_load_lds_dwordx4 v[146:147], off
	s_add_u32 m0, s21, 0xe000
	s_nop 0
	global_load_lds_dwordx4 v[148:149], off
	s_add_u32 m0, s21, 0x10000
	s_nop 0
	global_load_lds_dwordx4 v[150:151], off
	s_add_u32 m0, s21, 0x12000
	s_nop 0
	global_load_lds_dwordx4 v[152:153], off
	v_lshl_add_u64 v[146:147], v[146:147], 0, s[8:9]
	v_lshl_add_u64 v[148:149], v[148:149], 0, s[8:9]
	v_lshl_add_u64 v[150:151], v[150:151], 0, s[8:9]
	v_lshl_add_u64 v[152:153], v[152:153], 0, s[8:9]
	ds_read_b128 v[32:35], v170 offset:16384
	ds_read_b128 v[36:39], v174 offset:16384
	ds_read_b128 v[40:43], v171 offset:16384
	ds_read_b128 v[44:47], v175 offset:16384
	ds_read_b128 v[48:51], v172 offset:16384
	ds_read_b128 v[52:55], v176 offset:16384
	ds_read_b128 v[56:59], v173 offset:16384
	ds_read_b128 v[60:63], v177 offset:16384
	s_waitcnt lgkmcnt(6)
	v_mfma_f32_32x32x16_bf16 v[0:15], v[32:35], v[36:39], v[0:15]
	s_waitcnt lgkmcnt(4)
	v_mfma_f32_32x32x16_bf16 v[0:15], v[40:43], v[44:47], v[0:15]
	s_waitcnt lgkmcnt(2)
	v_mfma_f32_32x32x16_bf16 v[0:15], v[48:51], v[52:55], v[0:15]
	s_waitcnt lgkmcnt(0)
	v_mfma_f32_32x32x16_bf16 v[0:15], v[56:59], v[60:63], v[0:15]
	s_waitcnt vmcnt(4)
	s_barrier
; template <int K, bool SRC_F32>
; __device__ __forceinline__ void ctx_small_gemm(const bf16* __restrict__ WT, const bf16* __restrict__ act, const float* __restrict__ gate4,
;                                                const float* __restrict__ srcf, bf16* __restrict__ xbc) {
;     ...
; #pragma unroll 8
;     for (int k = 0; k < K / 2; k += 16) {
;       bf16x8 a = *reinterpret_cast<const bf16x8*>(ap + k), b = *reinterpret_cast<const bf16x8*>(bp + k);
;       acc = __builtin_amdgcn_mfma_f32_32x32x16_bf16(a, b, acc, 0, 0, 0);
;     }
;     __syncthreads();
;     if (kh == 1) {
; #pragma unroll
;       for (int r = 0; r < 16; ++r) red[(ob * 16 + r) * 64 + lane] = acc[r];
;     }
	s_add_u32 m0, s21, 0x14000
	s_nop 0
	global_load_lds_dwordx4 v[146:147], off
	s_add_u32 m0, s21, 0x16000
	s_nop 0
	global_load_lds_dwordx4 v[148:149], off
	s_add_u32 m0, s21, 0x18000
	s_nop 0
	global_load_lds_dwordx4 v[150:151], off
	s_add_u32 m0, s21, 0x1a000
	s_nop 0
	global_load_lds_dwordx4 v[152:153], off
	v_lshl_add_u64 v[146:147], v[146:147], 0, s[8:9]
	v_lshl_add_u64 v[148:149], v[148:149], 0, s[8:9]
	v_lshl_add_u64 v[150:151], v[150:151], 0, s[8:9]
	v_lshl_add_u64 v[152:153], v[152:153], 0, s[8:9]
	ds_read_b128 v[32:35], v154 offset:16384
	ds_read_b128 v[36:39], v158 offset:16384
	ds_read_b128 v[40:43], v155 offset:16384
	ds_read_b128 v[44:47], v159 offset:16384
	ds_read_b128 v[48:51], v156 offset:16384
	ds_read_b128 v[52:55], v160 offset:16384
	ds_read_b128 v[56:59], v157 offset:16384
	ds_read_b128 v[60:63], v161 offset:16384
	s_waitcnt lgkmcnt(6)
	v_mfma_f32_32x32x16_bf16 v[0:15], v[32:35], v[36:39], v[0:15]
	s_waitcnt lgkmcnt(4)
	v_mfma_f32_32x32x16_bf16 v[0:15], v[40:43], v[44:47], v[0:15]
	s_waitcnt lgkmcnt(2)
	v_mfma_f32_32x32x16_bf16 v[0:15], v[48:51], v[52:55], v[0:15]
	s_waitcnt lgkmcnt(0)
	v_mfma_f32_32x32x16_bf16 v[0:15], v[56:59], v[60:63], v[0:15]
	s_waitcnt vmcnt(4)
	s_barrier
	s_add_u32 m0, s21, 0x4000
	s_nop 0
	global_load_lds_dwordx4 v[146:147], off
	s_add_u32 m0, s21, 0x6000
	s_nop 0
	global_load_lds_dwordx4 v[148:149], off
	s_add_u32 m0, s21, 0x8000
	s_nop 0
	global_load_lds_dwordx4 v[150:151], off
	s_add_u32 m0, s21, 0xa000
	s_nop 0
	global_load_lds_dwordx4 v[152:153], off
	v_lshl_add_u64 v[146:147], v[146:147], 0, s[8:9]
	v_lshl_add_u64 v[148:149], v[148:149], 0, s[8:9]
	v_lshl_add_u64 v[150:151], v[150:151], 0, s[8:9]
	v_lshl_add_u64 v[152:153], v[152:153], 0, s[8:9]
	ds_read_b128 v[32:35], v154 offset:49152
	ds_read_b128 v[36:39], v158 offset:49152
	ds_read_b128 v[40:43], v155 offset:49152
	ds_read_b128 v[44:47], v159 offset:49152
	ds_read_b128 v[48:51], v156 offset:49152
	ds_read_b128 v[52:55], v160 offset:49152
	ds_read_b128 v[56:59], v157 offset:49152
	ds_read_b128 v[60:63], v161 offset:49152
	s_waitcnt lgkmcnt(6)
	v_mfma_f32_32x32x16_bf16 v[0:15], v[32:35], v[36:39], v[0:15]
	s_waitcnt lgkmcnt(4)
	v_mfma_f32_32x32x16_bf16 v[0:15], v[40:43], v[44:47], v[0:15]
	s_waitcnt lgkmcnt(2)
	v_mfma_f32_32x32x16_bf16 v[0:15], v[48:51], v[52:55], v[0:15]
	s_waitcnt lgkmcnt(0)
	v_mfma_f32_32x32x16_bf16 v[0:15], v[56:59], v[60:63], v[0:15]
	s_waitcnt vmcnt(4)
	s_barrier
	s_add_u32 m0, s21, 0xc000
	s_nop 0
	global_load_lds_dwordx4 v[146:147], off
	s_add_u32 m0, s21, 0xe000
	s_nop 0
	global_load_lds_dwordx4 v[148:149], off
	s_add_u32 m0, s21, 0x10000
	s_nop 0
	global_load_lds_dwordx4 v[150:151], off
	s_add_u32 m0, s21, 0x12000
	s_nop 0
	global_load_lds_dwordx4 v[152:153], off
	v_lshl_add_u64 v[146:147], v[146:147], 0, s[8:9]
	v_lshl_add_u64 v[148:149], v[148:149], 0, s[8:9]
	v_lshl_add_u64 v[150:151], v[150:151], 0, s[8:9]
	v_lshl_add_u64 v[152:153], v[152:153], 0, s[8:9]
	ds_read_b128 v[32:35], v170 offset:16384
	ds_read_b128 v[36:39], v174 offset:16384
	ds_read_b128 v[40:43], v171 offset:16384
	ds_read_b128 v[44:47], v175 offset:16384
	ds_read_b128 v[48:51], v172 offset:16384
	ds_read_b128 v[52:55], v176 offset:16384
	ds_read_b128 v[56:59], v173 offset:16384
	ds_read_b128 v[60:63], v177 offset:16384
	s_waitcnt lgkmcnt(6)
	v_mfma_f32_32x32x16_bf16 v[0:15], v[32:35], v[36:39], v[0:15]
	s_waitcnt lgkmcnt(4)
	v_mfma_f32_32x32x16_bf16 v[0:15], v[40:43], v[44:47], v[0:15]
	s_waitcnt lgkmcnt(2)
	v_mfma_f32_32x32x16_bf16 v[0:15], v[48:51], v[52:55], v[0:15]
	s_waitcnt lgkmcnt(0)
	v_mfma_f32_32x32x16_bf16 v[0:15], v[56:59], v[60:63], v[0:15]
	s_waitcnt vmcnt(4)
	s_barrier
	ds_read_b128 v[32:35], v154 offset:16384
	ds_read_b128 v[36:39], v158 offset:16384
	ds_read_b128 v[40:43], v155 offset:16384
	ds_read_b128 v[44:47], v159 offset:16384
	ds_read_b128 v[48:51], v156 offset:16384
	ds_read_b128 v[52:55], v160 offset:16384
	ds_read_b128 v[56:59], v157 offset:16384
	ds_read_b128 v[60:63], v161 offset:16384
	s_waitcnt lgkmcnt(6)
	v_mfma_f32_32x32x16_bf16 v[0:15], v[32:35], v[36:39], v[0:15]
	s_waitcnt lgkmcnt(4)
	v_mfma_f32_32x32x16_bf16 v[0:15], v[40:43], v[44:47], v[0:15]
	s_waitcnt lgkmcnt(2)
	v_mfma_f32_32x32x16_bf16 v[0:15], v[48:51], v[52:55], v[0:15]
	s_waitcnt lgkmcnt(0)
	v_mfma_f32_32x32x16_bf16 v[0:15], v[56:59], v[60:63], v[0:15]
	s_waitcnt vmcnt(0)
	s_barrier
	ds_read_b128 v[32:35], v154 offset:49152
	ds_read_b128 v[36:39], v158 offset:49152
	ds_read_b128 v[40:43], v155 offset:49152
	ds_read_b128 v[44:47], v159 offset:49152
	ds_read_b128 v[48:51], v156 offset:49152
	ds_read_b128 v[52:55], v160 offset:49152
	ds_read_b128 v[56:59], v157 offset:49152
	ds_read_b128 v[60:63], v161 offset:49152
	s_waitcnt lgkmcnt(6)
	v_mfma_f32_32x32x16_bf16 v[0:15], v[32:35], v[36:39], v[0:15]
	s_waitcnt lgkmcnt(4)
	v_mfma_f32_32x32x16_bf16 v[0:15], v[40:43], v[44:47], v[0:15]
	s_waitcnt lgkmcnt(2)
	v_mfma_f32_32x32x16_bf16 v[0:15], v[48:51], v[52:55], v[0:15]
	s_waitcnt lgkmcnt(0)
	v_mfma_f32_32x32x16_bf16 v[0:15], v[56:59], v[60:63], v[0:15]
	s_waitcnt lgkmcnt(0)
	s_barrier
	s_and_saveexec_b64 s[16:17], vcc
	s_cbranch_execz .LBB0_1003
	s_nop 6
	ds_write2st64_b32 v30, v0, v1 offset1:1
	ds_write2st64_b32 v30, v2, v3 offset0:2 offset1:3
	ds_write2st64_b32 v30, v4, v5 offset0:4 offset1:5
	ds_write2st64_b32 v30, v6, v7 offset0:6 offset1:7
	ds_write2st64_b32 v30, v8, v9 offset0:8 offset1:9
	ds_write2st64_b32 v30, v10, v11 offset0:10 offset1:11
	ds_write2st64_b32 v30, v12, v13 offset0:12 offset1:13
	ds_write2st64_b32 v30, v14, v15 offset0:14 offset1:15
; __device__ __forceinline__ unsigned short bf1(float a) { return (unsigned short)(cvtpk(a, 0.f) & 0xffffu); }
; __device__ __forceinline__ int crow(int r, int hi) { return (r & 3) + 8 * (r >> 2) + 4 * hi; }
; template <int K, bool SRC_F32>
; __device__ __forceinline__ void ctx_small_gemm(const bf16* __restrict__ WT, const bf16* __restrict__ act, const float* __restrict__ gate4,
;                                                const float* __restrict__ srcf, bf16* __restrict__ xbc) {
;     ...
;     if (kh == 0) {
;       const int f = f0 + r32;
;       const float gt = gate4[f];
;       unsigned short* xs = (unsigned short*)xbc;
; #pragma unroll
;       for (int r = 0; r < 16; ++r) {
;         const float v = acc[r] + red[(ob * 16 + r) * 64 + lane];
;         const size_t idx = (size_t)(tok0 + crow(r, hi)) * 1024 + f;
;         const float x = SRC_F32 ? srcf[idx] : __uint_as_float(((unsigned)xs[idx]) << 16);
;         xs[idx] = bf1(x + gt * v);
;       }
.LBB0_1003:
	s_or_b64 exec, exec, s[16:17]
	s_waitcnt lgkmcnt(0)
	s_barrier
	s_and_saveexec_b64 s[16:17], s[4:5]
	s_cbranch_execz .LBB0_998
	s_lshl_b32 s22, s20, 6
	s_and_b32 s22, s22, 0x3c0
	s_lshl_b32 s21, s20, 2
	v_or_b32_e32 v20, s22, v28
	s_andn2_b32 s21, s21, 63
	v_lshlrev_b32_e32 v52, 2, v20
	global_load_dword v53, v52, s[10:11]
	v_or3_b32 v22, s21, v26, v27
	v_lshlrev_b32_e32 v54, 1, v20
	v_lshl_add_u32 v54, v22, 11, v54
	v_add_u32_e32 v55, 0x1000, v54
	v_add_u32_e32 v56, 0x4000, v54
	v_add_u32_e32 v57, 0x5000, v54
	v_add_u32_e32 v58, 0x8000, v54
	v_add_u32_e32 v59, 0x9000, v54
	v_add_u32_e32 v60, 0xc000, v54
	v_add_u32_e32 v61, 0xd000, v54
	v_lshl_add_u32 v112, v22, 12, v52
	v_mov_b32_e32 v113, v112
	v_add_u32_e32 v114, 0x1000, v112
	v_add_u32_e32 v115, 0x2000, v112
	v_add_u32_e32 v116, 0x3000, v112
	v_add_u32_e32 v117, 0x8000, v112
	v_add_u32_e32 v118, 0x9000, v112
	v_add_u32_e32 v119, 0xa000, v112
	v_add_u32_e32 v120, 0xb000, v112
	v_add_u32_e32 v121, 0x10000, v112
	v_add_u32_e32 v122, 0x11000, v112
	v_add_u32_e32 v123, 0x12000, v112
	v_add_u32_e32 v124, 0x13000, v112
	v_add_u32_e32 v125, 0x18000, v112
	v_add_u32_e32 v126, 0x19000, v112
	v_add_u32_e32 v127, 0x1a000, v112
	v_add_u32_e32 v128, 0x1b000, v112
	global_load_dword v62, v113, s[12:13]
	global_load_dword v63, v114, s[12:13]
	global_load_dword v64, v115, s[12:13]
	global_load_dword v65, v116, s[12:13]
	global_load_dword v66, v117, s[12:13]
	global_load_dword v67, v118, s[12:13]
	global_load_dword v68, v119, s[12:13]
	global_load_dword v69, v120, s[12:13]
	global_load_dword v70, v121, s[12:13]
	global_load_dword v71, v122, s[12:13]
	global_load_dword v72, v123, s[12:13]
	global_load_dword v73, v124, s[12:13]
	global_load_dword v74, v125, s[12:13]
	global_load_dword v75, v126, s[12:13]
	global_load_dword v76, v127, s[12:13]
	global_load_dword v77, v128, s[12:13]
	ds_read_b32 v78, v31
	ds_read_b32 v79, v31 offset:256
	ds_read_b32 v80, v31 offset:512
	ds_read_b32 v81, v31 offset:768
	ds_read_b32 v82, v31 offset:1024
	ds_read_b32 v83, v31 offset:1280
	ds_read_b32 v84, v31 offset:1536
	ds_read_b32 v85, v31 offset:1792
	ds_read_b32 v86, v31 offset:2048
	ds_read_b32 v87, v31 offset:2304
	ds_read_b32 v88, v31 offset:2560
	ds_read_b32 v89, v31 offset:2816
	ds_read_b32 v90, v31 offset:3072
	ds_read_b32 v91, v31 offset:3328
	ds_read_b32 v92, v31 offset:3584
	ds_read_b32 v93, v31 offset:3840
	s_waitcnt vmcnt(15) lgkmcnt(15)
	v_add_f32_e32 v78, v0, v78
	v_fmac_f32_e32 v62, v53, v78
	v_cvt_pk_bf16_f32 v94, v62, v21
	s_waitcnt vmcnt(14) lgkmcnt(14)
	v_add_f32_e32 v79, v1, v79
	v_fmac_f32_e32 v63, v53, v79
	v_cvt_pk_bf16_f32 v95, v63, v21
	s_waitcnt vmcnt(13) lgkmcnt(13)
	v_add_f32_e32 v80, v2, v80
	v_fmac_f32_e32 v64, v53, v80
	v_cvt_pk_bf16_f32 v96, v64, v21
	s_waitcnt vmcnt(12) lgkmcnt(12)
	v_add_f32_e32 v81, v3, v81
	v_fmac_f32_e32 v65, v53, v81
	v_cvt_pk_bf16_f32 v97, v65, v21
	s_waitcnt vmcnt(11) lgkmcnt(11)
	v_add_f32_e32 v82, v4, v82
	v_fmac_f32_e32 v66, v53, v82
	v_cvt_pk_bf16_f32 v98, v66, v21
	s_waitcnt vmcnt(10) lgkmcnt(10)
	v_add_f32_e32 v83, v5, v83
	v_fmac_f32_e32 v67, v53, v83
	v_cvt_pk_bf16_f32 v99, v67, v21
	s_waitcnt vmcnt(9) lgkmcnt(9)
	v_add_f32_e32 v84, v6, v84
	v_fmac_f32_e32 v68, v53, v84
	v_cvt_pk_bf16_f32 v100, v68, v21
	s_waitcnt vmcnt(8) lgkmcnt(8)
	v_add_f32_e32 v85, v7, v85
	v_fmac_f32_e32 v69, v53, v85
	v_cvt_pk_bf16_f32 v101, v69, v21
	s_waitcnt vmcnt(7) lgkmcnt(7)
	v_add_f32_e32 v86, v8, v86
	v_fmac_f32_e32 v70, v53, v86
	v_cvt_pk_bf16_f32 v102, v70, v21
	s_waitcnt vmcnt(6) lgkmcnt(6)
	v_add_f32_e32 v87, v9, v87
	v_fmac_f32_e32 v71, v53, v87
	v_cvt_pk_bf16_f32 v103, v71, v21
	s_waitcnt vmcnt(5) lgkmcnt(5)
	v_add_f32_e32 v88, v10, v88
	v_fmac_f32_e32 v72, v53, v88
	v_cvt_pk_bf16_f32 v104, v72, v21
	s_waitcnt vmcnt(4) lgkmcnt(4)
	v_add_f32_e32 v89, v11, v89
	v_fmac_f32_e32 v73, v53, v89
	v_cvt_pk_bf16_f32 v105, v73, v21
	s_waitcnt vmcnt(3) lgkmcnt(3)
	v_add_f32_e32 v90, v12, v90
	v_fmac_f32_e32 v74, v53, v90
	v_cvt_pk_bf16_f32 v106, v74, v21
	s_waitcnt vmcnt(2) lgkmcnt(2)
	v_add_f32_e32 v91, v13, v91
	v_fmac_f32_e32 v75, v53, v91
	v_cvt_pk_bf16_f32 v107, v75, v21
	s_waitcnt vmcnt(1) lgkmcnt(1)
	v_add_f32_e32 v92, v14, v92
	v_fmac_f32_e32 v76, v53, v92
	v_cvt_pk_bf16_f32 v108, v76, v21
	s_waitcnt vmcnt(0) lgkmcnt(0)
	v_add_f32_e32 v93, v15, v93
	v_fmac_f32_e32 v77, v53, v93
	v_cvt_pk_bf16_f32 v109, v77, v21
	global_store_short v54, v94, s[14:15]
	global_store_short v54, v95, s[14:15] offset:2048
	global_store_short v55, v96, s[14:15]
	global_store_short v55, v97, s[14:15] offset:2048
	global_store_short v56, v98, s[14:15]
	global_store_short v56, v99, s[14:15] offset:2048
	global_store_short v57, v100, s[14:15]
	global_store_short v57, v101, s[14:15] offset:2048
	global_store_short v58, v102, s[14:15]
	global_store_short v58, v103, s[14:15] offset:2048
	global_store_short v59, v104, s[14:15]
	global_store_short v59, v105, s[14:15] offset:2048
	global_store_short v60, v106, s[14:15]
	global_store_short v60, v107, s[14:15] offset:2048
	global_store_short v61, v108, s[14:15]
	global_store_short v61, v109, s[14:15] offset:2048
	s_branch .LBB0_998

; __device__ __forceinline__ int tid_opaque() { int t = threadIdx.x; asm volatile("" : "+v"(t)); return t; }
; template <int K, bool SRC_F32>
; __device__ __forceinline__ void ctx_small_gemm(const bf16* __restrict__ WT, const bf16* __restrict__ act, const float* __restrict__ gate4,
;                                                const float* __restrict__ srcf, bf16* __restrict__ xbc) {
;   const int tid = tid_opaque(), wid = tid >> 6, lane = tid & 63, r32 = lane & 31, hi = lane >> 5;
;   const int kh = wid >> 2, ob = wid & 3, tb = ob >> 1, fb = ob & 1;
;   float* red = (float*)shm_raw;
;   for (int it = blockIdx.x; it < 256; it += gridDim.x) {
;     const int tok0 = (it >> 4) * 64 + tb * 32, f0 = (it & 15) * 64 + fb * 32;
;     const bf16* ap = act + (size_t)(tok0 + r32) * K + kh * (K / 2) + hi * 8;
;     const bf16* bp = WT + (size_t)(f0 + r32) * K + kh * (K / 2) + hi * 8;
.LBB0_1141:
	v_mov_b32_e32 v0, v192
	s_andn2_b64 vcc, exec, s[0:1]
	s_cbranch_vccnz .LBB0_1150
	v_and_b32_e32 v1, 63, v0
	v_lshl_add_u32 v5, v1, 2, 0
	v_ashrrev_i32_e32 v1, 8, v0
	v_lshrrev_b32_e32 v2, 2, v0
	v_and_b32_e32 v26, 32, v2
	v_mul_i32_i24_e32 v2, 0x580, v1
	s_movk_i32 s2, 0x100
	s_waitcnt lgkmcnt(0)
	s_add_u32 s0, s4, 0x305d000
	v_and_b32_e32 v4, 31, v0
	v_bfe_u32 v6, v0, 5, 1
	v_lshrrev_b32_e32 v7, 1, v0
	v_ashrrev_i32_e32 v3, 31, v2
	v_cmp_gt_u32_e64 s[6:7], s2, v0
	v_lshlrev_b32_e32 v0, 6, v0
	s_addc_u32 s1, s5, 0
	v_cmp_eq_u32_e32 vcc, 1, v1
	v_and_b32_e32 v8, 0xfffff000, v0
	v_and_b32_e32 v9, 0x3000, v0
	v_lshlrev_b64 v[0:1], 1, v[2:3]
	s_add_u32 s8, s4, 0xb300100
	v_lshl_or_b32 v0, v6, 4, v0
	s_addc_u32 s9, s5, 0
	v_lshl_add_u64 v[0:1], s[4:5], 0, v[0:1]
	v_lshrrev_b32_e32 v140, 4, v192
	v_xor_b32_e32 v141, v140, v192
	v_and_b32_e32 v141, 15, v141
	v_lshlrev_b32_e32 v141, 4, v141
	v_mov_b32_e32 v162, 0x1600
	v_mad_u32_u24 v140, v140, v162, v141
	v_mov_b32_e32 v141, 0
	v_lshl_add_u64 v[142:143], s[4:5], 0, v[140:141]
	v_lshl_add_u64 v[144:145], s[4:5], 0, v[140:141]
	v_mov_b32_e32 v162, 0x1a700100
	v_mov_b32_e32 v163, 0
	v_lshl_add_u64 v[142:143], v[142:143], 0, v[162:163]
	v_mov_b32_e32 v162, 0x2500000
	v_lshl_add_u64 v[144:145], v[144:145], 0, v[162:163]
	v_and_b32_e32 v162, 31, v192
	v_bfe_u32 v163, v192, 5, 1
	v_lshrrev_b32_e32 v164, 8, v192
	v_bfe_u32 v165, v192, 7, 1
	v_bfe_u32 v166, v192, 6, 1
	v_and_b32_e32 v167, 15, v162
	v_lshlrev_b32_e32 v167, 4, v167
	v_lshlrev_b32_e32 v168, 7, v164
	v_lshl_or_b32 v168, v163, 4, v168
	v_xor_b32_e32 v167, v167, v168
	v_lshl_or_b32 v169, v165, 5, v162
	v_lshl_or_b32 v154, v169, 8, v167
	v_lshl_or_b32 v169, v166, 5, v162
	v_lshl_or_b32 v158, v169, 8, v167
	v_add_u32_e32 v158, 0x4000, v158
	v_xor_b32_e32 v155, 32, v154
	v_xor_b32_e32 v159, 32, v158
	v_xor_b32_e32 v156, 64, v154
	v_xor_b32_e32 v160, 64, v158
	v_xor_b32_e32 v157, 96, v154
	v_xor_b32_e32 v161, 96, v158
	v_add_u32_e32 v170, 0x10000, v154
	v_add_u32_e32 v171, 0x10000, v155
	v_add_u32_e32 v172, 0x10000, v156
	v_add_u32_e32 v173, 0x10000, v157
	v_add_u32_e32 v174, 0x10000, v158
	v_add_u32_e32 v175, 0x10000, v159
	v_add_u32_e32 v176, 0x10000, v160
	v_add_u32_e32 v177, 0x10000, v161
	s_mov_b64 s[2:3], 0x1a700180
	s_mov_b64 s[4:5], 0x2500080
	v_lshlrev_b32_e32 v27, 2, v6
	v_and_or_b32 v28, v7, 32, v4
	v_lshl_add_u64 v[16:17], v[0:1], 0, s[2:3]
	v_or_b32_e32 v29, v26, v4
	s_lshl_b32 s2, s71, 2
	s_lshl_b32 s3, s74, 2
	v_lshl_add_u64 v[18:19], v[0:1], 0, s[4:5]
	s_movk_i32 s12, 0x1600
	s_mov_b64 s[4:5], 0x100
	v_add_u32_e32 v30, v5, v9
	v_mov_b32_e32 v21, 0
	v_add_u32_e32 v31, v5, v8
	s_mov_b32 s13, s71
	s_branch .LBB0_1144

; template <int K, bool SRC_F32>
; __device__ __forceinline__ void ctx_small_gemm(const bf16* __restrict__ WT, const bf16* __restrict__ act, const float* __restrict__ gate4,
;                                                const float* __restrict__ srcf, bf16* __restrict__ xbc) {
;     ...
;     const int tok0 = (it >> 4) * 64 + tb * 32, f0 = (it & 15) * 64 + fb * 32;
;     const bf16* ap = act + (size_t)(tok0 + r32) * K + kh * (K / 2) + hi * 8;
;     const bf16* bp = WT + (size_t)(f0 + r32) * K + kh * (K / 2) + hi * 8;
;     f32x16 acc = {};
; #pragma unroll 8
;     for (int k = 0; k < K / 2; k += 16) {
;       bf16x8 a = *reinterpret_cast<const bf16x8*>(ap + k), b = *reinterpret_cast<const bf16x8*>(bp + k);
;       acc = __builtin_amdgcn_mfma_f32_32x32x16_bf16(a, b, acc, 0, 0, 0);
;     }
.LBB0_1145:
	s_and_b32 s10, s2, 0xffffffc0
	s_mul_i32 s10, s10, 0x1600
	s_mov_b32 s11, 0
	v_lshl_add_u64 v[146:147], v[142:143], 0, s[10:11]
	s_lshl_b32 s10, s13, 6
	s_and_b32 s10, s10, 0x3c0
	s_mul_i32 s10, s10, 0x1600
	v_lshl_add_u64 v[150:151], v[144:145], 0, s[10:11]
	s_mov_b32 s10, 0x2c000
	v_lshl_add_u64 v[148:149], v[146:147], 0, s[10:11]
	v_lshl_add_u64 v[152:153], v[150:151], 0, s[10:11]
	v_lshrrev_b32_e32 v162, 6, v192
	v_lshlrev_b32_e32 v162, 10, v162
	s_nop 0
	v_readfirstlane_b32 s14, v162
	s_nop 3
	s_add_u32 m0, s14, 0x4000
	s_nop 0
	global_load_lds_dwordx4 v[146:147], off
	s_add_u32 m0, s14, 0x6000
	s_nop 0
	global_load_lds_dwordx4 v[148:149], off
	s_add_u32 m0, s14, 0x8000
	s_nop 0
	global_load_lds_dwordx4 v[150:151], off
	s_add_u32 m0, s14, 0xa000
	s_nop 0
	global_load_lds_dwordx4 v[152:153], off
	v_lshl_add_u64 v[146:147], v[146:147], 0, s[4:5]
	v_lshl_add_u64 v[148:149], v[148:149], 0, s[4:5]
	v_lshl_add_u64 v[150:151], v[150:151], 0, s[4:5]
	v_lshl_add_u64 v[152:153], v[152:153], 0, s[4:5]
	s_add_u32 m0, s14, 0xc000
	s_nop 0
	global_load_lds_dwordx4 v[146:147], off
	s_add_u32 m0, s14, 0xe000
	s_nop 0
	global_load_lds_dwordx4 v[148:149], off
	s_add_u32 m0, s14, 0x10000
	s_nop 0
	global_load_lds_dwordx4 v[150:151], off
	s_add_u32 m0, s14, 0x12000
	s_nop 0
	global_load_lds_dwordx4 v[152:153], off
	v_lshl_add_u64 v[146:147], v[146:147], 0, s[4:5]
	v_lshl_add_u64 v[148:149], v[148:149], 0, s[4:5]
	v_lshl_add_u64 v[150:151], v[150:151], 0, s[4:5]
	v_lshl_add_u64 v[152:153], v[152:153], 0, s[4:5]
	s_waitcnt vmcnt(4)
	s_barrier
	s_add_u32 m0, s14, 0x14000
	s_nop 0
	global_load_lds_dwordx4 v[146:147], off
	s_add_u32 m0, s14, 0x16000
	s_nop 0
	global_load_lds_dwordx4 v[148:149], off
	s_add_u32 m0, s14, 0x18000
	s_nop 0
	global_load_lds_dwordx4 v[150:151], off
	s_add_u32 m0, s14, 0x1a000
	s_nop 0
	global_load_lds_dwordx4 v[152:153], off
	v_lshl_add_u64 v[146:147], v[146:147], 0, s[4:5]
	v_lshl_add_u64 v[148:149], v[148:149], 0, s[4:5]
	v_lshl_add_u64 v[150:151], v[150:151], 0, s[4:5]
	v_lshl_add_u64 v[152:153], v[152:153], 0, s[4:5]
	ds_read_b128 v[32:35], v154 offset:16384
	ds_read_b128 v[36:39], v158 offset:16384
	ds_read_b128 v[40:43], v155 offset:16384
	ds_read_b128 v[44:47], v159 offset:16384
	ds_read_b128 v[48:51], v156 offset:16384
	ds_read_b128 v[52:55], v160 offset:16384
	ds_read_b128 v[56:59], v157 offset:16384
	ds_read_b128 v[60:63], v161 offset:16384
	s_waitcnt lgkmcnt(6)
	v_mfma_f32_32x32x16_bf16 v[0:15], v[32:35], v[36:39], v[0:15]
	s_waitcnt lgkmcnt(4)
	v_mfma_f32_32x32x16_bf16 v[0:15], v[40:43], v[44:47], v[0:15]
	s_waitcnt lgkmcnt(2)
	v_mfma_f32_32x32x16_bf16 v[0:15], v[48:51], v[52:55], v[0:15]
	s_waitcnt lgkmcnt(0)
	v_mfma_f32_32x32x16_bf16 v[0:15], v[56:59], v[60:63], v[0:15]
	s_waitcnt vmcnt(4)
	s_barrier
	s_add_u32 m0, s14, 0x4000
	s_nop 0
	global_load_lds_dwordx4 v[146:147], off
	s_add_u32 m0, s14, 0x6000
	s_nop 0
	global_load_lds_dwordx4 v[148:149], off
	s_add_u32 m0, s14, 0x8000
	s_nop 0
	global_load_lds_dwordx4 v[150:151], off
	s_add_u32 m0, s14, 0xa000
	s_nop 0
	global_load_lds_dwordx4 v[152:153], off
	v_lshl_add_u64 v[146:147], v[146:147], 0, s[4:5]
	v_lshl_add_u64 v[148:149], v[148:149], 0, s[4:5]
	v_lshl_add_u64 v[150:151], v[150:151], 0, s[4:5]
	v_lshl_add_u64 v[152:153], v[152:153], 0, s[4:5]
	ds_read_b128 v[32:35], v154 offset:49152
	ds_read_b128 v[36:39], v158 offset:49152
	ds_read_b128 v[40:43], v155 offset:49152
	ds_read_b128 v[44:47], v159 offset:49152
	ds_read_b128 v[48:51], v156 offset:49152
	ds_read_b128 v[52:55], v160 offset:49152
	ds_read_b128 v[56:59], v157 offset:49152
	ds_read_b128 v[60:63], v161 offset:49152
	s_waitcnt lgkmcnt(6)
	v_mfma_f32_32x32x16_bf16 v[0:15], v[32:35], v[36:39], v[0:15]
	s_waitcnt lgkmcnt(4)
	v_mfma_f32_32x32x16_bf16 v[0:15], v[40:43], v[44:47], v[0:15]
	s_waitcnt lgkmcnt(2)
	v_mfma_f32_32x32x16_bf16 v[0:15], v[48:51], v[52:55], v[0:15]
	s_waitcnt lgkmcnt(0)
	v_mfma_f32_32x32x16_bf16 v[0:15], v[56:59], v[60:63], v[0:15]
	s_waitcnt vmcnt(4)
	s_barrier
	s_add_u32 m0, s14, 0xc000
	s_nop 0
	global_load_lds_dwordx4 v[146:147], off
	s_add_u32 m0, s14, 0xe000
	s_nop 0
	global_load_lds_dwordx4 v[148:149], off
	s_add_u32 m0, s14, 0x10000
	s_nop 0
	global_load_lds_dwordx4 v[150:151], off
	s_add_u32 m0, s14, 0x12000
	s_nop 0
	global_load_lds_dwordx4 v[152:153], off
	v_lshl_add_u64 v[146:147], v[146:147], 0, s[4:5]
	v_lshl_add_u64 v[148:149], v[148:149], 0, s[4:5]
	v_lshl_add_u64 v[150:151], v[150:151], 0, s[4:5]
	v_lshl_add_u64 v[152:153], v[152:153], 0, s[4:5]
	ds_read_b128 v[32:35], v170 offset:16384
	ds_read_b128 v[36:39], v174 offset:16384
	ds_read_b128 v[40:43], v171 offset:16384
	ds_read_b128 v[44:47], v175 offset:16384
	ds_read_b128 v[48:51], v172 offset:16384
	ds_read_b128 v[52:55], v176 offset:16384
	ds_read_b128 v[56:59], v173 offset:16384
	ds_read_b128 v[60:63], v177 offset:16384
	s_waitcnt lgkmcnt(6)
	v_mfma_f32_32x32x16_bf16 v[0:15], v[32:35], v[36:39], v[0:15]
	s_waitcnt lgkmcnt(4)
	v_mfma_f32_32x32x16_bf16 v[0:15], v[40:43], v[44:47], v[0:15]
	s_waitcnt lgkmcnt(2)
	v_mfma_f32_32x32x16_bf16 v[0:15], v[48:51], v[52:55], v[0:15]
	s_waitcnt lgkmcnt(0)
	v_mfma_f32_32x32x16_bf16 v[0:15], v[56:59], v[60:63], v[0:15]
	s_waitcnt vmcnt(4)
	s_barrier
; template <int K, bool SRC_F32>
; __device__ __forceinline__ void ctx_small_gemm(const bf16* __restrict__ WT, const bf16* __restrict__ act, const float* __restrict__ gate4,
;                                                const float* __restrict__ srcf, bf16* __restrict__ xbc) {
;     ...
;     const int tok0 = (it >> 4) * 64 + tb * 32, f0 = (it & 15) * 64 + fb * 32;
;     const bf16* ap = act + (size_t)(tok0 + r32) * K + kh * (K / 2) + hi * 8;
;     const bf16* bp = WT + (size_t)(f0 + r32) * K + kh * (K / 2) + hi * 8;
;     f32x16 acc = {};
; #pragma unroll 8
;     for (int k = 0; k < K / 2; k += 16) {
;       bf16x8 a = *reinterpret_cast<const bf16x8*>(ap + k), b = *reinterpret_cast<const bf16x8*>(bp + k);
;       acc = __builtin_amdgcn_mfma_f32_32x32x16_bf16(a, b, acc, 0, 0, 0);
;     }
	s_add_u32 m0, s14, 0x14000
	s_nop 0
	global_load_lds_dwordx4 v[146:147], off
	s_add_u32 m0, s14, 0x16000
	s_nop 0
	global_load_lds_dwordx4 v[148:149], off
	s_add_u32 m0, s14, 0x18000
	s_nop 0
	global_load_lds_dwordx4 v[150:151], off
	s_add_u32 m0, s14, 0x1a000
	s_nop 0
	global_load_lds_dwordx4 v[152:153], off
	v_lshl_add_u64 v[146:147], v[146:147], 0, s[4:5]
	v_lshl_add_u64 v[148:149], v[148:149], 0, s[4:5]
	v_lshl_add_u64 v[150:151], v[150:151], 0, s[4:5]
	v_lshl_add_u64 v[152:153], v[152:153], 0, s[4:5]
	ds_read_b128 v[32:35], v154 offset:16384
	ds_read_b128 v[36:39], v158 offset:16384
	ds_read_b128 v[40:43], v155 offset:16384
	ds_read_b128 v[44:47], v159 offset:16384
	ds_read_b128 v[48:51], v156 offset:16384
	ds_read_b128 v[52:55], v160 offset:16384
	ds_read_b128 v[56:59], v157 offset:16384
	ds_read_b128 v[60:63], v161 offset:16384
	s_waitcnt lgkmcnt(6)
	v_mfma_f32_32x32x16_bf16 v[0:15], v[32:35], v[36:39], v[0:15]
	s_waitcnt lgkmcnt(4)
	v_mfma_f32_32x32x16_bf16 v[0:15], v[40:43], v[44:47], v[0:15]
	s_waitcnt lgkmcnt(2)
	v_mfma_f32_32x32x16_bf16 v[0:15], v[48:51], v[52:55], v[0:15]
	s_waitcnt lgkmcnt(0)
	v_mfma_f32_32x32x16_bf16 v[0:15], v[56:59], v[60:63], v[0:15]
	s_waitcnt vmcnt(4)
	s_barrier
	s_add_u32 m0, s14, 0x4000
	s_nop 0
	global_load_lds_dwordx4 v[146:147], off
	s_add_u32 m0, s14, 0x6000
	s_nop 0
	global_load_lds_dwordx4 v[148:149], off
	s_add_u32 m0, s14, 0x8000
	s_nop 0
	global_load_lds_dwordx4 v[150:151], off
	s_add_u32 m0, s14, 0xa000
	s_nop 0
	global_load_lds_dwordx4 v[152:153], off
	v_lshl_add_u64 v[146:147], v[146:147], 0, s[4:5]
	v_lshl_add_u64 v[148:149], v[148:149], 0, s[4:5]
	v_lshl_add_u64 v[150:151], v[150:151], 0, s[4:5]
	v_lshl_add_u64 v[152:153], v[152:153], 0, s[4:5]
	ds_read_b128 v[32:35], v154 offset:49152
	ds_read_b128 v[36:39], v158 offset:49152
	ds_read_b128 v[40:43], v155 offset:49152
	ds_read_b128 v[44:47], v159 offset:49152
	ds_read_b128 v[48:51], v156 offset:49152
	ds_read_b128 v[52:55], v160 offset:49152
	ds_read_b128 v[56:59], v157 offset:49152
	ds_read_b128 v[60:63], v161 offset:49152
	s_waitcnt lgkmcnt(6)
	v_mfma_f32_32x32x16_bf16 v[0:15], v[32:35], v[36:39], v[0:15]
	s_waitcnt lgkmcnt(4)
	v_mfma_f32_32x32x16_bf16 v[0:15], v[40:43], v[44:47], v[0:15]
	s_waitcnt lgkmcnt(2)
	v_mfma_f32_32x32x16_bf16 v[0:15], v[48:51], v[52:55], v[0:15]
	s_waitcnt lgkmcnt(0)
	v_mfma_f32_32x32x16_bf16 v[0:15], v[56:59], v[60:63], v[0:15]
	s_waitcnt vmcnt(4)
	s_barrier
	s_add_u32 m0, s14, 0xc000
	s_nop 0
	global_load_lds_dwordx4 v[146:147], off
	s_add_u32 m0, s14, 0xe000
	s_nop 0
	global_load_lds_dwordx4 v[148:149], off
	s_add_u32 m0, s14, 0x10000
	s_nop 0
	global_load_lds_dwordx4 v[150:151], off
	s_add_u32 m0, s14, 0x12000
	s_nop 0
	global_load_lds_dwordx4 v[152:153], off
	v_lshl_add_u64 v[146:147], v[146:147], 0, s[4:5]
	v_lshl_add_u64 v[148:149], v[148:149], 0, s[4:5]
	v_lshl_add_u64 v[150:151], v[150:151], 0, s[4:5]
	v_lshl_add_u64 v[152:153], v[152:153], 0, s[4:5]
	ds_read_b128 v[32:35], v170 offset:16384
	ds_read_b128 v[36:39], v174 offset:16384
	ds_read_b128 v[40:43], v171 offset:16384
	ds_read_b128 v[44:47], v175 offset:16384
	ds_read_b128 v[48:51], v172 offset:16384
	ds_read_b128 v[52:55], v176 offset:16384
	ds_read_b128 v[56:59], v173 offset:16384
	ds_read_b128 v[60:63], v177 offset:16384
	s_waitcnt lgkmcnt(6)
	v_mfma_f32_32x32x16_bf16 v[0:15], v[32:35], v[36:39], v[0:15]
	s_waitcnt lgkmcnt(4)
	v_mfma_f32_32x32x16_bf16 v[0:15], v[40:43], v[44:47], v[0:15]
	s_waitcnt lgkmcnt(2)
	v_mfma_f32_32x32x16_bf16 v[0:15], v[48:51], v[52:55], v[0:15]
	s_waitcnt lgkmcnt(0)
	v_mfma_f32_32x32x16_bf16 v[0:15], v[56:59], v[60:63], v[0:15]
	s_waitcnt vmcnt(4)
	s_barrier
	s_add_u32 m0, s14, 0x14000
	s_nop 0
	global_load_lds_dwordx4 v[146:147], off
	s_add_u32 m0, s14, 0x16000
	s_nop 0
	global_load_lds_dwordx4 v[148:149], off
	s_add_u32 m0, s14, 0x18000
	s_nop 0
	global_load_lds_dwordx4 v[150:151], off
	s_add_u32 m0, s14, 0x1a000
	s_nop 0
	global_load_lds_dwordx4 v[152:153], off
	v_lshl_add_u64 v[146:147], v[146:147], 0, s[4:5]
	v_lshl_add_u64 v[148:149], v[148:149], 0, s[4:5]
	v_lshl_add_u64 v[150:151], v[150:151], 0, s[4:5]
	v_lshl_add_u64 v[152:153], v[152:153], 0, s[4:5]
	ds_read_b128 v[32:35], v154 offset:16384
	ds_read_b128 v[36:39], v158 offset:16384
	ds_read_b128 v[40:43], v155 offset:16384
	ds_read_b128 v[44:47], v159 offset:16384
	ds_read_b128 v[48:51], v156 offset:16384
	ds_read_b128 v[52:55], v160 offset:16384
	ds_read_b128 v[56:59], v157 offset:16384
	ds_read_b128 v[60:63], v161 offset:16384
	s_waitcnt lgkmcnt(6)
	v_mfma_f32_32x32x16_bf16 v[0:15], v[32:35], v[36:39], v[0:15]
	s_waitcnt lgkmcnt(4)
	v_mfma_f32_32x32x16_bf16 v[0:15], v[40:43], v[44:47], v[0:15]
	s_waitcnt lgkmcnt(2)
	v_mfma_f32_32x32x16_bf16 v[0:15], v[48:51], v[52:55], v[0:15]
	s_waitcnt lgkmcnt(0)
	v_mfma_f32_32x32x16_bf16 v[0:15], v[56:59], v[60:63], v[0:15]
	s_waitcnt vmcnt(4)
	s_barrier
	s_add_u32 m0, s14, 0x4000
	s_nop 0
	global_load_lds_dwordx4 v[146:147], off
	s_add_u32 m0, s14, 0x6000
	s_nop 0
	global_load_lds_dwordx4 v[148:149], off
	s_add_u32 m0, s14, 0x8000
	s_nop 0
	global_load_lds_dwordx4 v[150:151], off
	s_add_u32 m0, s14, 0xa000
	s_nop 0
	global_load_lds_dwordx4 v[152:153], off
	v_lshl_add_u64 v[146:147], v[146:147], 0, s[4:5]
	v_lshl_add_u64 v[148:149], v[148:149], 0, s[4:5]
	v_lshl_add_u64 v[150:151], v[150:151], 0, s[4:5]
	v_lshl_add_u64 v[152:153], v[152:153], 0, s[4:5]
	ds_read_b128 v[32:35], v154 offset:49152
	ds_read_b128 v[36:39], v158 offset:49152
	ds_read_b128 v[40:43], v155 offset:49152
	ds_read_b128 v[44:47], v159 offset:49152
	ds_read_b128 v[48:51], v156 offset:49152
	ds_read_b128 v[52:55], v160 offset:49152
	ds_read_b128 v[56:59], v157 offset:49152
	ds_read_b128 v[60:63], v161 offset:49152
	s_waitcnt lgkmcnt(6)
	v_mfma_f32_32x32x16_bf16 v[0:15], v[32:35], v[36:39], v[0:15]
	s_waitcnt lgkmcnt(4)
	v_mfma_f32_32x32x16_bf16 v[0:15], v[40:43], v[44:47], v[0:15]
	s_waitcnt lgkmcnt(2)
	v_mfma_f32_32x32x16_bf16 v[0:15], v[48:51], v[52:55], v[0:15]
	s_waitcnt lgkmcnt(0)
	v_mfma_f32_32x32x16_bf16 v[0:15], v[56:59], v[60:63], v[0:15]
	s_waitcnt vmcnt(4)
	s_barrier
; template <int K, bool SRC_F32>
; __device__ __forceinline__ void ctx_small_gemm(const bf16* __restrict__ WT, const bf16* __restrict__ act, const float* __restrict__ gate4,
;                                                const float* __restrict__ srcf, bf16* __restrict__ xbc) {
;     ...
;     const int tok0 = (it >> 4) * 64 + tb * 32, f0 = (it & 15) * 64 + fb * 32;
;     const bf16* ap = act + (size_t)(tok0 + r32) * K + kh * (K / 2) + hi * 8;
;     const bf16* bp = WT + (size_t)(f0 + r32) * K + kh * (K / 2) + hi * 8;
;     f32x16 acc = {};
; #pragma unroll 8
;     for (int k = 0; k < K / 2; k += 16) {
;       bf16x8 a = *reinterpret_cast<const bf16x8*>(ap + k), b = *reinterpret_cast<const bf16x8*>(bp + k);
;       acc = __builtin_amdgcn_mfma_f32_32x32x16_bf16(a, b, acc, 0, 0, 0);
;     }
	s_add_u32 m0, s14, 0xc000
	s_nop 0
	global_load_lds_dwordx4 v[146:147], off
	s_add_u32 m0, s14, 0xe000
	s_nop 0
	global_load_lds_dwordx4 v[148:149], off
	s_add_u32 m0, s14, 0x10000
	s_nop 0
	global_load_lds_dwordx4 v[150:151], off
	s_add_u32 m0, s14, 0x12000
	s_nop 0
	global_load_lds_dwordx4 v[152:153], off
	v_lshl_add_u64 v[146:147], v[146:147], 0, s[4:5]
	v_lshl_add_u64 v[148:149], v[148:149], 0, s[4:5]
	v_lshl_add_u64 v[150:151], v[150:151], 0, s[4:5]
	v_lshl_add_u64 v[152:153], v[152:153], 0, s[4:5]
	ds_read_b128 v[32:35], v170 offset:16384
	ds_read_b128 v[36:39], v174 offset:16384
	ds_read_b128 v[40:43], v171 offset:16384
	ds_read_b128 v[44:47], v175 offset:16384
	ds_read_b128 v[48:51], v172 offset:16384
	ds_read_b128 v[52:55], v176 offset:16384
	ds_read_b128 v[56:59], v173 offset:16384
	ds_read_b128 v[60:63], v177 offset:16384
	s_waitcnt lgkmcnt(6)
	v_mfma_f32_32x32x16_bf16 v[0:15], v[32:35], v[36:39], v[0:15]
	s_waitcnt lgkmcnt(4)
	v_mfma_f32_32x32x16_bf16 v[0:15], v[40:43], v[44:47], v[0:15]
	s_waitcnt lgkmcnt(2)
	v_mfma_f32_32x32x16_bf16 v[0:15], v[48:51], v[52:55], v[0:15]
	s_waitcnt lgkmcnt(0)
	v_mfma_f32_32x32x16_bf16 v[0:15], v[56:59], v[60:63], v[0:15]
	s_waitcnt vmcnt(4)
	s_barrier
	s_add_u32 m0, s14, 0x14000
	s_nop 0
	global_load_lds_dwordx4 v[146:147], off
	s_add_u32 m0, s14, 0x16000
	s_nop 0
	global_load_lds_dwordx4 v[148:149], off
	s_add_u32 m0, s14, 0x18000
	s_nop 0
	global_load_lds_dwordx4 v[150:151], off
	s_add_u32 m0, s14, 0x1a000
	s_nop 0
	global_load_lds_dwordx4 v[152:153], off
	v_lshl_add_u64 v[146:147], v[146:147], 0, s[4:5]
	v_lshl_add_u64 v[148:149], v[148:149], 0, s[4:5]
	v_lshl_add_u64 v[150:151], v[150:151], 0, s[4:5]
	v_lshl_add_u64 v[152:153], v[152:153], 0, s[4:5]
	ds_read_b128 v[32:35], v154 offset:16384
	ds_read_b128 v[36:39], v158 offset:16384
	ds_read_b128 v[40:43], v155 offset:16384
	ds_read_b128 v[44:47], v159 offset:16384
	ds_read_b128 v[48:51], v156 offset:16384
	ds_read_b128 v[52:55], v160 offset:16384
	ds_read_b128 v[56:59], v157 offset:16384
	ds_read_b128 v[60:63], v161 offset:16384
	s_waitcnt lgkmcnt(6)
	v_mfma_f32_32x32x16_bf16 v[0:15], v[32:35], v[36:39], v[0:15]
	s_waitcnt lgkmcnt(4)
	v_mfma_f32_32x32x16_bf16 v[0:15], v[40:43], v[44:47], v[0:15]
	s_waitcnt lgkmcnt(2)
	v_mfma_f32_32x32x16_bf16 v[0:15], v[48:51], v[52:55], v[0:15]
	s_waitcnt lgkmcnt(0)
	v_mfma_f32_32x32x16_bf16 v[0:15], v[56:59], v[60:63], v[0:15]
	s_waitcnt vmcnt(4)
	s_barrier
	s_add_u32 m0, s14, 0x4000
	s_nop 0
	global_load_lds_dwordx4 v[146:147], off
	s_add_u32 m0, s14, 0x6000
	s_nop 0
	global_load_lds_dwordx4 v[148:149], off
	s_add_u32 m0, s14, 0x8000
	s_nop 0
	global_load_lds_dwordx4 v[150:151], off
	s_add_u32 m0, s14, 0xa000
	s_nop 0
	global_load_lds_dwordx4 v[152:153], off
	v_lshl_add_u64 v[146:147], v[146:147], 0, s[4:5]
	v_lshl_add_u64 v[148:149], v[148:149], 0, s[4:5]
	v_lshl_add_u64 v[150:151], v[150:151], 0, s[4:5]
	v_lshl_add_u64 v[152:153], v[152:153], 0, s[4:5]
	ds_read_b128 v[32:35], v154 offset:49152
	ds_read_b128 v[36:39], v158 offset:49152
	ds_read_b128 v[40:43], v155 offset:49152
	ds_read_b128 v[44:47], v159 offset:49152
	ds_read_b128 v[48:51], v156 offset:49152
	ds_read_b128 v[52:55], v160 offset:49152
	ds_read_b128 v[56:59], v157 offset:49152
	ds_read_b128 v[60:63], v161 offset:49152
	s_waitcnt lgkmcnt(6)
	v_mfma_f32_32x32x16_bf16 v[0:15], v[32:35], v[36:39], v[0:15]
	s_waitcnt lgkmcnt(4)
	v_mfma_f32_32x32x16_bf16 v[0:15], v[40:43], v[44:47], v[0:15]
	s_waitcnt lgkmcnt(2)
	v_mfma_f32_32x32x16_bf16 v[0:15], v[48:51], v[52:55], v[0:15]
	s_waitcnt lgkmcnt(0)
	v_mfma_f32_32x32x16_bf16 v[0:15], v[56:59], v[60:63], v[0:15]
	s_waitcnt vmcnt(4)
	s_barrier
	s_add_u32 m0, s14, 0xc000
	s_nop 0
	global_load_lds_dwordx4 v[146:147], off
	s_add_u32 m0, s14, 0xe000
	s_nop 0
	global_load_lds_dwordx4 v[148:149], off
	s_add_u32 m0, s14, 0x10000
	s_nop 0
	global_load_lds_dwordx4 v[150:151], off
	s_add_u32 m0, s14, 0x12000
	s_nop 0
	global_load_lds_dwordx4 v[152:153], off
	v_lshl_add_u64 v[146:147], v[146:147], 0, s[4:5]
	v_lshl_add_u64 v[148:149], v[148:149], 0, s[4:5]
	v_lshl_add_u64 v[150:151], v[150:151], 0, s[4:5]
	v_lshl_add_u64 v[152:153], v[152:153], 0, s[4:5]
	ds_read_b128 v[32:35], v170 offset:16384
	ds_read_b128 v[36:39], v174 offset:16384
	ds_read_b128 v[40:43], v171 offset:16384
	ds_read_b128 v[44:47], v175 offset:16384
	ds_read_b128 v[48:51], v172 offset:16384
	ds_read_b128 v[52:55], v176 offset:16384
	ds_read_b128 v[56:59], v173 offset:16384
	ds_read_b128 v[60:63], v177 offset:16384
	s_waitcnt lgkmcnt(6)
	v_mfma_f32_32x32x16_bf16 v[0:15], v[32:35], v[36:39], v[0:15]
	s_waitcnt lgkmcnt(4)
	v_mfma_f32_32x32x16_bf16 v[0:15], v[40:43], v[44:47], v[0:15]
	s_waitcnt lgkmcnt(2)
	v_mfma_f32_32x32x16_bf16 v[0:15], v[48:51], v[52:55], v[0:15]
	s_waitcnt lgkmcnt(0)
	v_mfma_f32_32x32x16_bf16 v[0:15], v[56:59], v[60:63], v[0:15]
	s_waitcnt vmcnt(4)
	s_barrier
	s_add_u32 m0, s14, 0x14000
	s_nop 0
	global_load_lds_dwordx4 v[146:147], off
	s_add_u32 m0, s14, 0x16000
	s_nop 0
	global_load_lds_dwordx4 v[148:149], off
	s_add_u32 m0, s14, 0x18000
	s_nop 0
	global_load_lds_dwordx4 v[150:151], off
	s_add_u32 m0, s14, 0x1a000
	s_nop 0
	global_load_lds_dwordx4 v[152:153], off
	v_lshl_add_u64 v[146:147], v[146:147], 0, s[4:5]
	v_lshl_add_u64 v[148:149], v[148:149], 0, s[4:5]
	v_lshl_add_u64 v[150:151], v[150:151], 0, s[4:5]
	v_lshl_add_u64 v[152:153], v[152:153], 0, s[4:5]
	ds_read_b128 v[32:35], v154 offset:16384
	ds_read_b128 v[36:39], v158 offset:16384
	ds_read_b128 v[40:43], v155 offset:16384
	ds_read_b128 v[44:47], v159 offset:16384
	ds_read_b128 v[48:51], v156 offset:16384
	ds_read_b128 v[52:55], v160 offset:16384
	ds_read_b128 v[56:59], v157 offset:16384
	ds_read_b128 v[60:63], v161 offset:16384
	s_waitcnt lgkmcnt(6)
	v_mfma_f32_32x32x16_bf16 v[0:15], v[32:35], v[36:39], v[0:15]
	s_waitcnt lgkmcnt(4)
	v_mfma_f32_32x32x16_bf16 v[0:15], v[40:43], v[44:47], v[0:15]
	s_waitcnt lgkmcnt(2)
	v_mfma_f32_32x32x16_bf16 v[0:15], v[48:51], v[52:55], v[0:15]
	s_waitcnt lgkmcnt(0)
	v_mfma_f32_32x32x16_bf16 v[0:15], v[56:59], v[60:63], v[0:15]
	s_waitcnt vmcnt(4)
	s_barrier
; template <int K, bool SRC_F32>
; __device__ __forceinline__ void ctx_small_gemm(const bf16* __restrict__ WT, const bf16* __restrict__ act, const float* __restrict__ gate4,
;                                                const float* __restrict__ srcf, bf16* __restrict__ xbc) {
;     ...
;     const int tok0 = (it >> 4) * 64 + tb * 32, f0 = (it & 15) * 64 + fb * 32;
;     const bf16* ap = act + (size_t)(tok0 + r32) * K + kh * (K / 2) + hi * 8;
;     const bf16* bp = WT + (size_t)(f0 + r32) * K + kh * (K / 2) + hi * 8;
;     f32x16 acc = {};
; #pragma unroll 8
;     for (int k = 0; k < K / 2; k += 16) {
;       bf16x8 a = *reinterpret_cast<const bf16x8*>(ap + k), b = *reinterpret_cast<const bf16x8*>(bp + k);
;       acc = __builtin_amdgcn_mfma_f32_32x32x16_bf16(a, b, acc, 0, 0, 0);
;     }
	s_add_u32 m0, s14, 0x4000
	s_nop 0
	global_load_lds_dwordx4 v[146:147], off
	s_add_u32 m0, s14, 0x6000
	s_nop 0
	global_load_lds_dwordx4 v[148:149], off
	s_add_u32 m0, s14, 0x8000
	s_nop 0
	global_load_lds_dwordx4 v[150:151], off
	s_add_u32 m0, s14, 0xa000
	s_nop 0
	global_load_lds_dwordx4 v[152:153], off
	v_lshl_add_u64 v[146:147], v[146:147], 0, s[4:5]
	v_lshl_add_u64 v[148:149], v[148:149], 0, s[4:5]
	v_lshl_add_u64 v[150:151], v[150:151], 0, s[4:5]
	v_lshl_add_u64 v[152:153], v[152:153], 0, s[4:5]
	ds_read_b128 v[32:35], v154 offset:49152
	ds_read_b128 v[36:39], v158 offset:49152
	ds_read_b128 v[40:43], v155 offset:49152
	ds_read_b128 v[44:47], v159 offset:49152
	ds_read_b128 v[48:51], v156 offset:49152
	ds_read_b128 v[52:55], v160 offset:49152
	ds_read_b128 v[56:59], v157 offset:49152
	ds_read_b128 v[60:63], v161 offset:49152
	s_waitcnt lgkmcnt(6)
	v_mfma_f32_32x32x16_bf16 v[0:15], v[32:35], v[36:39], v[0:15]
	s_waitcnt lgkmcnt(4)
	v_mfma_f32_32x32x16_bf16 v[0:15], v[40:43], v[44:47], v[0:15]
	s_waitcnt lgkmcnt(2)
	v_mfma_f32_32x32x16_bf16 v[0:15], v[48:51], v[52:55], v[0:15]
	s_waitcnt lgkmcnt(0)
	v_mfma_f32_32x32x16_bf16 v[0:15], v[56:59], v[60:63], v[0:15]
	s_waitcnt vmcnt(4)
	s_barrier
	s_add_u32 m0, s14, 0xc000
	s_nop 0
	global_load_lds_dwordx4 v[146:147], off
	s_add_u32 m0, s14, 0xe000
	s_nop 0
	global_load_lds_dwordx4 v[148:149], off
	s_add_u32 m0, s14, 0x10000
	s_nop 0
	global_load_lds_dwordx4 v[150:151], off
	s_add_u32 m0, s14, 0x12000
	s_nop 0
	global_load_lds_dwordx4 v[152:153], off
	v_lshl_add_u64 v[146:147], v[146:147], 0, s[4:5]
	v_lshl_add_u64 v[148:149], v[148:149], 0, s[4:5]
	v_lshl_add_u64 v[150:151], v[150:151], 0, s[4:5]
	v_lshl_add_u64 v[152:153], v[152:153], 0, s[4:5]
	ds_read_b128 v[32:35], v170 offset:16384
	ds_read_b128 v[36:39], v174 offset:16384
	ds_read_b128 v[40:43], v171 offset:16384
	ds_read_b128 v[44:47], v175 offset:16384
	ds_read_b128 v[48:51], v172 offset:16384
	ds_read_b128 v[52:55], v176 offset:16384
	ds_read_b128 v[56:59], v173 offset:16384
	ds_read_b128 v[60:63], v177 offset:16384
	s_waitcnt lgkmcnt(6)
	v_mfma_f32_32x32x16_bf16 v[0:15], v[32:35], v[36:39], v[0:15]
	s_waitcnt lgkmcnt(4)
	v_mfma_f32_32x32x16_bf16 v[0:15], v[40:43], v[44:47], v[0:15]
	s_waitcnt lgkmcnt(2)
	v_mfma_f32_32x32x16_bf16 v[0:15], v[48:51], v[52:55], v[0:15]
	s_waitcnt lgkmcnt(0)
	v_mfma_f32_32x32x16_bf16 v[0:15], v[56:59], v[60:63], v[0:15]
	s_waitcnt vmcnt(4)
	s_barrier
	s_add_u32 m0, s14, 0x14000
	s_nop 0
	global_load_lds_dwordx4 v[146:147], off
	s_add_u32 m0, s14, 0x16000
	s_nop 0
	global_load_lds_dwordx4 v[148:149], off
	s_add_u32 m0, s14, 0x18000
	s_nop 0
	global_load_lds_dwordx4 v[150:151], off
	s_add_u32 m0, s14, 0x1a000
	s_nop 0
	global_load_lds_dwordx4 v[152:153], off
	v_lshl_add_u64 v[146:147], v[146:147], 0, s[4:5]
	v_lshl_add_u64 v[148:149], v[148:149], 0, s[4:5]
	v_lshl_add_u64 v[150:151], v[150:151], 0, s[4:5]
	v_lshl_add_u64 v[152:153], v[152:153], 0, s[4:5]
	ds_read_b128 v[32:35], v154 offset:16384
	ds_read_b128 v[36:39], v158 offset:16384
	ds_read_b128 v[40:43], v155 offset:16384
	ds_read_b128 v[44:47], v159 offset:16384
	ds_read_b128 v[48:51], v156 offset:16384
	ds_read_b128 v[52:55], v160 offset:16384
	ds_read_b128 v[56:59], v157 offset:16384
	ds_read_b128 v[60:63], v161 offset:16384
	s_waitcnt lgkmcnt(6)
	v_mfma_f32_32x32x16_bf16 v[0:15], v[32:35], v[36:39], v[0:15]
	s_waitcnt lgkmcnt(4)
	v_mfma_f32_32x32x16_bf16 v[0:15], v[40:43], v[44:47], v[0:15]
	s_waitcnt lgkmcnt(2)
	v_mfma_f32_32x32x16_bf16 v[0:15], v[48:51], v[52:55], v[0:15]
	s_waitcnt lgkmcnt(0)
	v_mfma_f32_32x32x16_bf16 v[0:15], v[56:59], v[60:63], v[0:15]
	s_waitcnt vmcnt(4)
	s_barrier
	s_add_u32 m0, s14, 0x4000
	s_nop 0
	global_load_lds_dwordx4 v[146:147], off
	s_add_u32 m0, s14, 0x6000
	s_nop 0
	global_load_lds_dwordx4 v[148:149], off
	s_add_u32 m0, s14, 0x8000
	s_nop 0
	global_load_lds_dwordx4 v[150:151], off
	s_add_u32 m0, s14, 0xa000
	s_nop 0
	global_load_lds_dwordx4 v[152:153], off
	v_lshl_add_u64 v[146:147], v[146:147], 0, s[4:5]
	v_lshl_add_u64 v[148:149], v[148:149], 0, s[4:5]
	v_lshl_add_u64 v[150:151], v[150:151], 0, s[4:5]
	v_lshl_add_u64 v[152:153], v[152:153], 0, s[4:5]
	ds_read_b128 v[32:35], v154 offset:49152
	ds_read_b128 v[36:39], v158 offset:49152
	ds_read_b128 v[40:43], v155 offset:49152
	ds_read_b128 v[44:47], v159 offset:49152
	ds_read_b128 v[48:51], v156 offset:49152
	ds_read_b128 v[52:55], v160 offset:49152
	ds_read_b128 v[56:59], v157 offset:49152
	ds_read_b128 v[60:63], v161 offset:49152
	s_waitcnt lgkmcnt(6)
	v_mfma_f32_32x32x16_bf16 v[0:15], v[32:35], v[36:39], v[0:15]
	s_waitcnt lgkmcnt(4)
	v_mfma_f32_32x32x16_bf16 v[0:15], v[40:43], v[44:47], v[0:15]
	s_waitcnt lgkmcnt(2)
	v_mfma_f32_32x32x16_bf16 v[0:15], v[48:51], v[52:55], v[0:15]
	s_waitcnt lgkmcnt(0)
	v_mfma_f32_32x32x16_bf16 v[0:15], v[56:59], v[60:63], v[0:15]
	s_waitcnt vmcnt(4)
	s_barrier
	s_add_u32 m0, s14, 0xc000
	s_nop 0
	global_load_lds_dwordx4 v[146:147], off
	s_add_u32 m0, s14, 0xe000
	s_nop 0
	global_load_lds_dwordx4 v[148:149], off
	s_add_u32 m0, s14, 0x10000
	s_nop 0
	global_load_lds_dwordx4 v[150:151], off
	s_add_u32 m0, s14, 0x12000
	s_nop 0
	global_load_lds_dwordx4 v[152:153], off
	v_lshl_add_u64 v[146:147], v[146:147], 0, s[4:5]
	v_lshl_add_u64 v[148:149], v[148:149], 0, s[4:5]
	v_lshl_add_u64 v[150:151], v[150:151], 0, s[4:5]
	v_lshl_add_u64 v[152:153], v[152:153], 0, s[4:5]
	ds_read_b128 v[32:35], v170 offset:16384
	ds_read_b128 v[36:39], v174 offset:16384
	ds_read_b128 v[40:43], v171 offset:16384
	ds_read_b128 v[44:47], v175 offset:16384
	ds_read_b128 v[48:51], v172 offset:16384
	ds_read_b128 v[52:55], v176 offset:16384
	ds_read_b128 v[56:59], v173 offset:16384
	ds_read_b128 v[60:63], v177 offset:16384
	s_waitcnt lgkmcnt(6)
	v_mfma_f32_32x32x16_bf16 v[0:15], v[32:35], v[36:39], v[0:15]
	s_waitcnt lgkmcnt(4)
	v_mfma_f32_32x32x16_bf16 v[0:15], v[40:43], v[44:47], v[0:15]
	s_waitcnt lgkmcnt(2)
	v_mfma_f32_32x32x16_bf16 v[0:15], v[48:51], v[52:55], v[0:15]
	s_waitcnt lgkmcnt(0)
	v_mfma_f32_32x32x16_bf16 v[0:15], v[56:59], v[60:63], v[0:15]
	s_waitcnt vmcnt(4)
	s_barrier
; template <int K, bool SRC_F32>
; __device__ __forceinline__ void ctx_small_gemm(const bf16* __restrict__ WT, const bf16* __restrict__ act, const float* __restrict__ gate4,
;                                                const float* __restrict__ srcf, bf16* __restrict__ xbc) {
;     ...
; #pragma unroll 8
;     for (int k = 0; k < K / 2; k += 16) {
;       bf16x8 a = *reinterpret_cast<const bf16x8*>(ap + k), b = *reinterpret_cast<const bf16x8*>(bp + k);
;       acc = __builtin_amdgcn_mfma_f32_32x32x16_bf16(a, b, acc, 0, 0, 0);
;     }
;     __syncthreads();
;     if (kh == 1) {
; #pragma unroll
;       for (int r = 0; r < 16; ++r) red[(ob * 16 + r) * 64 + lane] = acc[r];
;     }
	s_add_u32 m0, s14, 0x14000
	s_nop 0
	global_load_lds_dwordx4 v[146:147], off
	s_add_u32 m0, s14, 0x16000
	s_nop 0
	global_load_lds_dwordx4 v[148:149], off
	s_add_u32 m0, s14, 0x18000
	s_nop 0
	global_load_lds_dwordx4 v[150:151], off
	s_add_u32 m0, s14, 0x1a000
	s_nop 0
	global_load_lds_dwordx4 v[152:153], off
	v_lshl_add_u64 v[146:147], v[146:147], 0, s[4:5]
	v_lshl_add_u64 v[148:149], v[148:149], 0, s[4:5]
	v_lshl_add_u64 v[150:151], v[150:151], 0, s[4:5]
	v_lshl_add_u64 v[152:153], v[152:153], 0, s[4:5]
	ds_read_b128 v[32:35], v154 offset:16384
	ds_read_b128 v[36:39], v158 offset:16384
	ds_read_b128 v[40:43], v155 offset:16384
	ds_read_b128 v[44:47], v159 offset:16384
	ds_read_b128 v[48:51], v156 offset:16384
	ds_read_b128 v[52:55], v160 offset:16384
	ds_read_b128 v[56:59], v157 offset:16384
	ds_read_b128 v[60:63], v161 offset:16384
	s_waitcnt lgkmcnt(6)
	v_mfma_f32_32x32x16_bf16 v[0:15], v[32:35], v[36:39], v[0:15]
	s_waitcnt lgkmcnt(4)
	v_mfma_f32_32x32x16_bf16 v[0:15], v[40:43], v[44:47], v[0:15]
	s_waitcnt lgkmcnt(2)
	v_mfma_f32_32x32x16_bf16 v[0:15], v[48:51], v[52:55], v[0:15]
	s_waitcnt lgkmcnt(0)
	v_mfma_f32_32x32x16_bf16 v[0:15], v[56:59], v[60:63], v[0:15]
	s_waitcnt vmcnt(4)
	s_barrier
	s_add_u32 m0, s14, 0x4000
	s_nop 0
	global_load_lds_dwordx4 v[146:147], off
	s_add_u32 m0, s14, 0x6000
	s_nop 0
	global_load_lds_dwordx4 v[148:149], off
	s_add_u32 m0, s14, 0x8000
	s_nop 0
	global_load_lds_dwordx4 v[150:151], off
	s_add_u32 m0, s14, 0xa000
	s_nop 0
	global_load_lds_dwordx4 v[152:153], off
	v_lshl_add_u64 v[146:147], v[146:147], 0, s[4:5]
	v_lshl_add_u64 v[148:149], v[148:149], 0, s[4:5]
	v_lshl_add_u64 v[150:151], v[150:151], 0, s[4:5]
	v_lshl_add_u64 v[152:153], v[152:153], 0, s[4:5]
	ds_read_b128 v[32:35], v154 offset:49152
	ds_read_b128 v[36:39], v158 offset:49152
	ds_read_b128 v[40:43], v155 offset:49152
	ds_read_b128 v[44:47], v159 offset:49152
	ds_read_b128 v[48:51], v156 offset:49152
	ds_read_b128 v[52:55], v160 offset:49152
	ds_read_b128 v[56:59], v157 offset:49152
	ds_read_b128 v[60:63], v161 offset:49152
	s_waitcnt lgkmcnt(6)
	v_mfma_f32_32x32x16_bf16 v[0:15], v[32:35], v[36:39], v[0:15]
	s_waitcnt lgkmcnt(4)
	v_mfma_f32_32x32x16_bf16 v[0:15], v[40:43], v[44:47], v[0:15]
	s_waitcnt lgkmcnt(2)
	v_mfma_f32_32x32x16_bf16 v[0:15], v[48:51], v[52:55], v[0:15]
	s_waitcnt lgkmcnt(0)
	v_mfma_f32_32x32x16_bf16 v[0:15], v[56:59], v[60:63], v[0:15]
	s_waitcnt vmcnt(4)
	s_barrier
	ds_read_b128 v[32:35], v170 offset:16384
	ds_read_b128 v[36:39], v174 offset:16384
	ds_read_b128 v[40:43], v171 offset:16384
	ds_read_b128 v[44:47], v175 offset:16384
	ds_read_b128 v[48:51], v172 offset:16384
	ds_read_b128 v[52:55], v176 offset:16384
	ds_read_b128 v[56:59], v173 offset:16384
	ds_read_b128 v[60:63], v177 offset:16384
	s_waitcnt lgkmcnt(6)
	v_mfma_f32_32x32x16_bf16 v[0:15], v[32:35], v[36:39], v[0:15]
	s_waitcnt lgkmcnt(4)
	v_mfma_f32_32x32x16_bf16 v[0:15], v[40:43], v[44:47], v[0:15]
	s_waitcnt lgkmcnt(2)
	v_mfma_f32_32x32x16_bf16 v[0:15], v[48:51], v[52:55], v[0:15]
	s_waitcnt lgkmcnt(0)
	v_mfma_f32_32x32x16_bf16 v[0:15], v[56:59], v[60:63], v[0:15]
	s_waitcnt vmcnt(0)
	s_barrier
	ds_read_b128 v[32:35], v154 offset:16384
	ds_read_b128 v[36:39], v158 offset:16384
	ds_read_b128 v[40:43], v155 offset:16384
	ds_read_b128 v[44:47], v159 offset:16384
	ds_read_b128 v[48:51], v156 offset:16384
	ds_read_b128 v[52:55], v160 offset:16384
	ds_read_b128 v[56:59], v157 offset:16384
	ds_read_b128 v[60:63], v161 offset:16384
	s_waitcnt lgkmcnt(6)
	v_mfma_f32_32x32x16_bf16 v[0:15], v[32:35], v[36:39], v[0:15]
	s_waitcnt lgkmcnt(4)
	v_mfma_f32_32x32x16_bf16 v[0:15], v[40:43], v[44:47], v[0:15]
	s_waitcnt lgkmcnt(2)
	v_mfma_f32_32x32x16_bf16 v[0:15], v[48:51], v[52:55], v[0:15]
	s_waitcnt lgkmcnt(0)
	v_mfma_f32_32x32x16_bf16 v[0:15], v[56:59], v[60:63], v[0:15]
	s_barrier
	s_and_saveexec_b64 s[10:11], vcc
	s_cbranch_execz .LBB0_1148
	s_nop 7
	ds_write2st64_b32 v30, v0, v1 offset1:1
	ds_write2st64_b32 v30, v2, v3 offset0:2 offset1:3
	ds_write2st64_b32 v30, v4, v5 offset0:4 offset1:5
	ds_write2st64_b32 v30, v6, v7 offset0:6 offset1:7
	ds_write2st64_b32 v30, v8, v9 offset0:8 offset1:9
	ds_write2st64_b32 v30, v10, v11 offset0:10 offset1:11
	ds_write2st64_b32 v30, v12, v13 offset0:12 offset1:13
	ds_write2st64_b32 v30, v14, v15 offset0:14 offset1:15
; __device__ __forceinline__ unsigned short bf1(float a) { return (unsigned short)(cvtpk(a, 0.f) & 0xffffu); }
; __device__ __forceinline__ int crow(int r, int hi) { return (r & 3) + 8 * (r >> 2) + 4 * hi; }
; template <int K, bool SRC_F32>
; __device__ __forceinline__ void ctx_small_gemm(const bf16* __restrict__ WT, const bf16* __restrict__ act, const float* __restrict__ gate4,
;                                                const float* __restrict__ srcf, bf16* __restrict__ xbc) {
;     ...
;     if (kh == 0) {
;       const int f = f0 + r32;
;       const float gt = gate4[f];
;       unsigned short* xs = (unsigned short*)xbc;
; #pragma unroll
;       for (int r = 0; r < 16; ++r) {
;         const float v = acc[r] + red[(ob * 16 + r) * 64 + lane];
;         const size_t idx = (size_t)(tok0 + crow(r, hi)) * 1024 + f;
;         const float x = SRC_F32 ? srcf[idx] : __uint_as_float(((unsigned)xs[idx]) << 16);
;         xs[idx] = bf1(x + gt * v);
;       }
.LBB0_1148:
	s_or_b64 exec, exec, s[10:11]
	s_waitcnt lgkmcnt(0)
	s_barrier
	s_and_saveexec_b64 s[10:11], s[6:7]
	s_cbranch_execz .LBB0_1143
	s_lshl_b32 s14, s13, 2
	s_andn2_b32 s14, s14, 63
	v_or3_b32 v24, s14, v26, v27
	v_lshlrev_b32_e32 v52, 2, v20
	global_load_dword v53, v52, s[0:1]
	v_lshlrev_b32_e32 v54, 1, v20
	v_lshl_add_u32 v54, v24, 11, v54
	v_add_u32_e32 v55, 0x1000, v54
	v_add_u32_e32 v56, 0x4000, v54
	v_add_u32_e32 v57, 0x5000, v54
	v_add_u32_e32 v58, 0x8000, v54
	v_add_u32_e32 v59, 0x9000, v54
	v_add_u32_e32 v60, 0xc000, v54
	v_add_u32_e32 v61, 0xd000, v54
	global_load_ushort v62, v54, s[8:9]
	global_load_ushort v63, v54, s[8:9] offset:2048
	global_load_ushort v64, v55, s[8:9]
	global_load_ushort v65, v55, s[8:9] offset:2048
	global_load_ushort v66, v56, s[8:9]
	global_load_ushort v67, v56, s[8:9] offset:2048
	global_load_ushort v68, v57, s[8:9]
	global_load_ushort v69, v57, s[8:9] offset:2048
	global_load_ushort v70, v58, s[8:9]
	global_load_ushort v71, v58, s[8:9] offset:2048
	global_load_ushort v72, v59, s[8:9]
	global_load_ushort v73, v59, s[8:9] offset:2048
	global_load_ushort v74, v60, s[8:9]
	global_load_ushort v75, v60, s[8:9] offset:2048
	global_load_ushort v76, v61, s[8:9]
	global_load_ushort v77, v61, s[8:9] offset:2048
	ds_read_b32 v78, v31
	ds_read_b32 v79, v31 offset:256
	ds_read_b32 v80, v31 offset:512
	ds_read_b32 v81, v31 offset:768
	ds_read_b32 v82, v31 offset:1024
	ds_read_b32 v83, v31 offset:1280
	ds_read_b32 v84, v31 offset:1536
	ds_read_b32 v85, v31 offset:1792
	ds_read_b32 v86, v31 offset:2048
	ds_read_b32 v87, v31 offset:2304
	ds_read_b32 v88, v31 offset:2560
	ds_read_b32 v89, v31 offset:2816
	ds_read_b32 v90, v31 offset:3072
	ds_read_b32 v91, v31 offset:3328
	ds_read_b32 v92, v31 offset:3584
	ds_read_b32 v93, v31 offset:3840
	s_waitcnt vmcnt(15) lgkmcnt(15)
	v_add_f32_e32 v78, v0, v78
	v_lshlrev_b32_e32 v62, 16, v62
	v_fmac_f32_e32 v62, v53, v78
	v_cvt_pk_bf16_f32 v94, v62, v21
	s_waitcnt vmcnt(14) lgkmcnt(14)
	v_add_f32_e32 v79, v1, v79
	v_lshlrev_b32_e32 v63, 16, v63
	v_fmac_f32_e32 v63, v53, v79
	v_cvt_pk_bf16_f32 v95, v63, v21
	s_waitcnt vmcnt(13) lgkmcnt(13)
	v_add_f32_e32 v80, v2, v80
	v_lshlrev_b32_e32 v64, 16, v64
	v_fmac_f32_e32 v64, v53, v80
	v_cvt_pk_bf16_f32 v96, v64, v21
	s_waitcnt vmcnt(12) lgkmcnt(12)
	v_add_f32_e32 v81, v3, v81
	v_lshlrev_b32_e32 v65, 16, v65
	v_fmac_f32_e32 v65, v53, v81
	v_cvt_pk_bf16_f32 v97, v65, v21
	s_waitcnt vmcnt(11) lgkmcnt(11)
	v_add_f32_e32 v82, v4, v82
	v_lshlrev_b32_e32 v66, 16, v66
	v_fmac_f32_e32 v66, v53, v82
	v_cvt_pk_bf16_f32 v98, v66, v21
	s_waitcnt vmcnt(10) lgkmcnt(10)
	v_add_f32_e32 v83, v5, v83
	v_lshlrev_b32_e32 v67, 16, v67
	v_fmac_f32_e32 v67, v53, v83
	v_cvt_pk_bf16_f32 v99, v67, v21
	s_waitcnt vmcnt(9) lgkmcnt(9)
	v_add_f32_e32 v84, v6, v84
	v_lshlrev_b32_e32 v68, 16, v68
	v_fmac_f32_e32 v68, v53, v84
	v_cvt_pk_bf16_f32 v100, v68, v21
	s_waitcnt vmcnt(8) lgkmcnt(8)
	v_add_f32_e32 v85, v7, v85
	v_lshlrev_b32_e32 v69, 16, v69
	v_fmac_f32_e32 v69, v53, v85
	v_cvt_pk_bf16_f32 v101, v69, v21
	s_waitcnt vmcnt(7) lgkmcnt(7)
	v_add_f32_e32 v86, v8, v86
	v_lshlrev_b32_e32 v70, 16, v70
	v_fmac_f32_e32 v70, v53, v86
	v_cvt_pk_bf16_f32 v102, v70, v21
	s_waitcnt vmcnt(6) lgkmcnt(6)
	v_add_f32_e32 v87, v9, v87
	v_lshlrev_b32_e32 v71, 16, v71
	v_fmac_f32_e32 v71, v53, v87
	v_cvt_pk_bf16_f32 v103, v71, v21
	s_waitcnt vmcnt(5) lgkmcnt(5)
	v_add_f32_e32 v88, v10, v88
	v_lshlrev_b32_e32 v72, 16, v72
	v_fmac_f32_e32 v72, v53, v88
	v_cvt_pk_bf16_f32 v104, v72, v21
	s_waitcnt vmcnt(4) lgkmcnt(4)
	v_add_f32_e32 v89, v11, v89
	v_lshlrev_b32_e32 v73, 16, v73
	v_fmac_f32_e32 v73, v53, v89
	v_cvt_pk_bf16_f32 v105, v73, v21
	s_waitcnt vmcnt(3) lgkmcnt(3)
	v_add_f32_e32 v90, v12, v90
	v_lshlrev_b32_e32 v74, 16, v74
	v_fmac_f32_e32 v74, v53, v90
	v_cvt_pk_bf16_f32 v106, v74, v21
	s_waitcnt vmcnt(2) lgkmcnt(2)
	v_add_f32_e32 v91, v13, v91
	v_lshlrev_b32_e32 v75, 16, v75
	v_fmac_f32_e32 v75, v53, v91
	v_cvt_pk_bf16_f32 v107, v75, v21
	s_waitcnt vmcnt(1) lgkmcnt(1)
	v_add_f32_e32 v92, v14, v92
	v_lshlrev_b32_e32 v76, 16, v76
	v_fmac_f32_e32 v76, v53, v92
	v_cvt_pk_bf16_f32 v108, v76, v21
	s_waitcnt vmcnt(0) lgkmcnt(0)
	v_add_f32_e32 v93, v15, v93
	v_lshlrev_b32_e32 v77, 16, v77
	v_fmac_f32_e32 v77, v53, v93
	v_cvt_pk_bf16_f32 v109, v77, v21
	global_store_short v54, v94, s[8:9]
	global_store_short v54, v95, s[8:9] offset:2048
	global_store_short v55, v96, s[8:9]
	global_store_short v55, v97, s[8:9] offset:2048
	global_store_short v56, v98, s[8:9]
	global_store_short v56, v99, s[8:9] offset:2048
	global_store_short v57, v100, s[8:9]
	global_store_short v57, v101, s[8:9] offset:2048
	global_store_short v58, v102, s[8:9]
	global_store_short v58, v103, s[8:9] offset:2048
	global_store_short v59, v104, s[8:9]
	global_store_short v59, v105, s[8:9] offset:2048
	global_store_short v60, v106, s[8:9]
	global_store_short v60, v107, s[8:9] offset:2048
	global_store_short v61, v108, s[8:9]
	global_store_short v61, v109, s[8:9] offset:2048
	s_branch .LBB0_1143
